# swa main loop: Q-load waits moved before the loop so later iterations do not wait for the previous iteration's store acks
# speedup vs baseline: 1.0012x; 1.0012x over previous
.LBB0_301:
	s_or_b64 exec, exec, s[6:7]
	v_ashrrev_i32_e32 v0, 7, v8
	v_lshl_add_u32 v2, s5, 2, v0
	v_add_u32_e32 v0, 1, v2
	v_cvt_f32_i32_e32 v13, v0
	v_add_u32_e32 v0, s36, v2
	v_ashrrev_i32_e32 v1, 31, v0
	v_and_b32_e32 v146, 64, v8
	v_lshl_add_u64 v[0:1], v[0:1], 2, v[10:11]
	s_or_b32 s5, s10, s11
	v_lshlrev_b32_e32 v12, 6, v2
	global_load_dword v147, v[0:1], off
	v_or3_b32 v3, v146, s5, v145
	v_add_u32_e32 v0, 0xe00, v12
	v_ashrrev_i32_e32 v9, 31, v3
	v_ashrrev_i32_e32 v114, 8, v0
	v_ashrrev_i32_e32 v115, 31, v114
	v_alignbit_b32 v0, v9, v3, 8
	v_mad_u64_u32 v[0:1], s[6:7], v0, 49, v[114:115]
	v_bfe_u32 v5, v8, 5, 1
	v_mad_u32_u24 v1, v9, 49, v1
	v_lshlrev_b32_e32 v4, 3, v5
	v_and_b32_e32 v11, 0xc0, v12
	v_lshlrev_b64 v[0:1], 17, v[0:1]
	v_lshlrev_b32_e32 v2, 9, v3
	v_or_b32_e32 v10, v11, v4
	v_lshl_add_u64 v[0:1], v[112:113], 0, v[0:1]
	v_and_b32_e32 v166, 0x1fe00, v2
	v_lshl_add_u64 v[0:1], v[0:1], 0, v[166:167]
	v_lshlrev_b32_e32 v166, 1, v10
	v_lshl_add_u64 v[14:15], v[0:1], 0, v[166:167]
	global_load_dwordx4 v[0:3], v[14:15], off
	global_load_dwordx4 v[100:103], v[14:15], off offset:32
	global_load_dwordx4 v[104:107], v[14:15], off offset:64
	global_load_dwordx4 v[108:111], v[14:15], off offset:96
	v_and_b32_e32 v9, 0xff, v8
	v_ashrrev_i32_e32 v14, 4, v8
	v_mov_b32_e32 v8, s92
	v_and_b32_e32 v15, -16, v14
	v_mad_u32_u24 v16, v9, s93, v8
	v_lshl_add_u32 v19, v15, 2, v16
	s_waitcnt vmcnt(5)
	v_cmp_gt_i32_e32 vcc, 0x100, v208
	s_and_saveexec_b64 s[6:7], vcc
	ds_write_b32 v45, v44
	s_or_b64 exec, exec, s[6:7]
	s_waitcnt lgkmcnt(0)
	s_barrier
	v_lshlrev_b32_e32 v17, 1, v9
	ds_read2_b32 v[8:9], v19 offset1:1
	v_add_u32_e32 v18, 0, v17
	v_mul_lo_u32 v15, v15, s69
	v_add_u32_e32 v20, v18, v15
	v_add3_u32 v15, 0, v15, v17
	s_waitcnt lgkmcnt(0)
	ds_write_b16 v20, v8 offset:36864
	ds_write_b16_d16_hi v15, v8 offset:37384
	ds_write_b16 v15, v9 offset:37904
	ds_write_b16_d16_hi v15, v9 offset:38424
	ds_read2_b32 v[8:9], v19 offset0:2 offset1:3
	s_waitcnt lgkmcnt(0)
	ds_write_b16 v15, v8 offset:38944
	ds_write_b16_d16_hi v15, v8 offset:39464
	ds_write_b16 v15, v9 offset:39984
	ds_write_b16_d16_hi v15, v9 offset:40504
	ds_read2_b32 v[8:9], v19 offset0:4 offset1:5
	s_waitcnt lgkmcnt(0)
	ds_write_b16 v15, v8 offset:41024
	ds_write_b16_d16_hi v15, v8 offset:41544
	ds_write_b16 v15, v9 offset:42064
	ds_write_b16_d16_hi v15, v9 offset:42584
	ds_read2_b32 v[8:9], v19 offset0:6 offset1:7
	s_waitcnt lgkmcnt(0)
	ds_write_b16 v15, v8 offset:43104
	ds_write_b16_d16_hi v15, v8 offset:43624
	ds_write_b16 v15, v9 offset:44144
	ds_write_b16_d16_hi v15, v9 offset:44664
	ds_read2_b32 v[8:9], v19 offset0:8 offset1:9
	s_waitcnt lgkmcnt(0)
	ds_write_b16 v15, v8 offset:45184
	ds_write_b16_d16_hi v15, v8 offset:45704
	ds_write_b16 v15, v9 offset:46224
	ds_write_b16_d16_hi v15, v9 offset:46744
	ds_read2_b32 v[8:9], v19 offset0:10 offset1:11
	s_waitcnt lgkmcnt(0)
	ds_write_b16 v15, v8 offset:47264
	ds_write_b16_d16_hi v15, v8 offset:47784
	ds_write_b16 v15, v9 offset:48304
	ds_write_b16_d16_hi v15, v9 offset:48824
	ds_read2_b32 v[8:9], v19 offset0:12 offset1:13
	s_waitcnt lgkmcnt(0)
	ds_write_b16 v15, v8 offset:49344
	ds_write_b16_d16_hi v15, v8 offset:49864
	ds_write_b16 v15, v9 offset:50384
	ds_write_b16_d16_hi v15, v9 offset:50904
	ds_read_b32 v8, v19 offset:56
	s_waitcnt lgkmcnt(0)
	ds_write_b16 v15, v8 offset:51424
	ds_write_b16_d16_hi v15, v8 offset:51944
	v_or_b32_e32 v8, 15, v14
	v_lshl_add_u32 v9, v8, 2, v16
	ds_read_b32 v9, v9
	v_mul_lo_u32 v8, v8, s69
	v_add_u32_e32 v14, v18, v8
	v_add3_u32 v8, 0, v8, v17
	s_mov_b32 s6, 0x42fc0000
	s_waitcnt lgkmcnt(0)
	ds_write_b16_d16_hi v8, v9 offset:37384
	v_cmp_lt_f32_e32 vcc, s6, v13
	v_mov_b32_e32 v8, 0x42800000
	ds_write_b16 v14, v9 offset:36864
	v_cndmask_b32_e32 v8, 0, v8, vcc
	v_sub_f32_e32 v8, v8, v13
	v_exp_f32_e32 v8, v8
	v_not_b32_e32 v9, 63
	v_cndmask_b32_e32 v9, 0, v9, vcc
	s_cmp_lg_u32 s76, 0
	v_ldexp_f32 v117, v8, v9
	v_lshlrev_b32_e32 v9, 2, v5
	v_lshlrev_b32_e32 v5, 4, v5
	s_cselect_b64 s[6:7], -1, 0
	s_add_i32 s85, 0, 0x11400
	v_add_u32_e32 v148, 0, v5
	v_add_u32_e32 v149, s85, v5
	v_or_b32_e32 v5, 2, v9
	v_cmp_gt_u32_e64 s[14:15], v5, v145
	v_or_b32_e32 v5, 3, v9
	v_cmp_gt_u32_e64 s[18:19], v5, v145
	v_or_b32_e32 v5, 9, v9
	v_cmp_gt_u32_e64 s[26:27], v5, v145
	v_or_b32_e32 v5, 10, v9
	v_cmp_gt_u32_e64 s[30:31], v5, v145
	v_or_b32_e32 v5, 11, v9
	s_mov_b32 s33, s36
	v_cmp_gt_u32_e64 s[36:37], v5, v145
	v_or_b32_e32 v5, 17, v9
	v_cmp_gt_u32_e64 s[44:45], v5, v145
	v_or_b32_e32 v5, 18, v9
	v_cmp_gt_u32_e64 s[48:49], v5, v145
	v_or_b32_e32 v5, 19, v9
	v_cmp_gt_u32_e64 s[52:53], v5, v145
	v_or_b32_e32 v5, 25, v9
	v_add_u32_e32 v8, 0x1100, v12
	v_and_b32_e32 v13, 64, v214
	v_cmp_gt_u32_e64 s[60:61], v5, v145
	v_or_b32_e32 v5, 26, v9
	s_mov_b64 s[2:3], s[64:65]
	v_ashrrev_i32_e32 v118, 8, v8
	v_or_b32_e32 v8, v11, v9
	v_xor_b32_e32 v11, 32, v214
	v_add_u32_e32 v13, 64, v13
	v_cmp_gt_u32_e64 s[64:65], v5, v145
	v_or_b32_e32 v5, 27, v9
	v_cmp_lt_i32_e32 vcc, v11, v13
	v_ashrrev_i32_e32 v13, 31, v12
	v_cmp_gt_u32_e64 s[68:69], v5, v145
	v_or_b32_e32 v5, s76, v146
	v_lshl_add_u64 v[6:7], v[12:13], 1, v[6:7]
	v_or_b32_e32 v150, 8, v9
	v_or_b32_e32 v152, 16, v9
	v_or_b32_e32 v154, 24, v9
	v_cmp_eq_u32_e64 s[74:75], 0, v5
	v_mov_b32_e32 v5, v167
	v_cndmask_b32_e32 v11, v214, v11, vcc
	v_cmp_gt_u32_e64 s[8:9], v9, v145
	v_cmp_ge_u32_e32 vcc, v9, v145
	v_cmp_gt_u32_e64 s[22:23], v150, v145
	v_cmp_gt_u32_e64 s[40:41], v152, v145
	v_cmp_gt_u32_e64 s[56:57], v154, v145
	v_cmp_lt_u32_e64 s[72:73], v9, v145
	v_mul_u32_u24_e32 v9, 0x208, v145
	v_lshl_add_u64 v[6:7], v[6:7], 0, v[4:5]
	s_mov_b64 s[82:83], 0x21cc2800
	s_mov_b32 s0, s66
	s_mov_b64 s[78:79], s[62:63]
	s_mov_b32 s96, 0
	v_ashrrev_i32_e32 v119, 31, v118
	v_lshlrev_b32_e32 v144, 2, v11
	s_and_b64 s[10:11], s[6:7], s[8:9]
	s_and_b64 s[12:13], s[6:7], vcc
	s_and_b64 s[16:17], s[6:7], s[14:15]
	s_and_b64 s[20:21], s[6:7], s[18:19]
	v_lshl_add_u32 v151, v150, 2, s85
	s_and_b64 s[24:25], s[6:7], s[22:23]
	s_and_b64 s[28:29], s[6:7], s[26:27]
	s_and_b64 s[34:35], s[6:7], s[30:31]
	s_and_b64 s[38:39], s[6:7], s[36:37]
	v_lshl_add_u32 v153, v152, 2, s85
	s_and_b64 s[42:43], s[6:7], s[40:41]
	s_and_b64 s[46:47], s[6:7], s[44:45]
	s_and_b64 s[50:51], s[6:7], s[48:49]
	s_and_b64 s[54:55], s[6:7], s[52:53]
	v_lshl_add_u32 v155, v154, 2, s85
	s_and_b64 s[58:59], s[6:7], s[56:57]
	s_and_b64 s[62:63], s[6:7], s[60:61]
	s_and_b64 s[66:67], s[6:7], s[64:65]
	s_and_b64 s[70:71], s[6:7], s[68:69]
	v_lshl_add_u64 v[120:121], v[6:7], 0, s[82:83]
	v_add3_u32 v156, 0, v9, v4
	s_mov_b64 s[82:83], -1
	v_lshlrev_b32_e32 v122, 1, v10
	v_lshlrev_b32_e32 v124, 1, v8
	s_waitcnt lgkmcnt(0)
	s_barrier
	s_waitcnt vmcnt(0)
.LBB0_302:
	v_or_b32_e32 v157, s96, v146
	v_or_b32_e32 v116, v157, v145
	v_or_b32_e32 v140, s5, v116
	v_ashrrev_i32_e32 v141, 31, v140
	s_sub_i32 s96, 32, s96
	v_lshl_add_u64 v[4:5], v[140:141], 0, s[96:97]
	v_alignbit_b32 v6, v5, v4, 8
	v_mad_u64_u32 v[6:7], vcc, v6, 49, v[114:115]
	v_mad_u32_u24 v7, v5, 49, v7
	v_lshlrev_b64 v[6:7], 17, v[6:7]
	v_lshlrev_b32_e32 v4, 9, v4
	v_lshl_add_u64 v[6:7], v[112:113], 0, v[6:7]
	v_and_b32_e32 v166, 0x1fe00, v4
	v_lshl_add_u64 v[4:5], v[6:7], 0, v[166:167]
	v_mov_b32_e32 v123, v167
	v_lshl_add_u64 v[4:5], v[4:5], 0, v[122:123]
	global_load_dwordx4 v[84:87], v[4:5], off
	global_load_dwordx4 v[88:91], v[4:5], off offset:32
	global_load_dwordx4 v[92:95], v[4:5], off offset:64
	global_load_dwordx4 v[96:99], v[4:5], off offset:96
	v_alignbit_b32 v4, v141, v140, 8
	v_mad_u64_u32 v[4:5], vcc, v4, 49, v[118:119]
	v_mad_u32_u24 v5, v141, 49, v5
	v_lshlrev_b64 v[4:5], 17, v[4:5]
	v_lshlrev_b32_e32 v6, 9, v140
	v_lshl_add_u64 v[4:5], v[112:113], 0, v[4:5]
	v_and_b32_e32 v166, 0x1fe00, v6
	v_lshl_add_u64 v[4:5], v[4:5], 0, v[166:167]
	v_mov_b32_e32 v125, v167
	v_lshl_add_u64 v[4:5], v[4:5], 0, v[124:125]
	v_mad_u32_u24 v123, v116, s94, v148
	global_load_dwordx2 v[142:143], v[4:5], off
	global_load_dwordx2 v[138:139], v[4:5], off offset:16
	global_load_dwordx2 v[136:137], v[4:5], off offset:32
	global_load_dwordx2 v[134:135], v[4:5], off offset:48
	global_load_dwordx2 v[132:133], v[4:5], off offset:64
	global_load_dwordx2 v[130:131], v[4:5], off offset:80
	global_load_dwordx2 v[128:129], v[4:5], off offset:96
	global_load_dwordx2 v[126:127], v[4:5], off offset:112
	ds_read_b128 v[4:7], v123
	ds_read_b128 v[8:11], v123 offset:32
	s_waitcnt lgkmcnt(1)
	v_mfma_f32_32x32x16_bf16 v[64:79], v[4:7], v[0:3], 0
	ds_read_b128 v[4:7], v123 offset:64
	ds_read_b128 v[158:161], v123 offset:18464
	s_mov_b32 s96, 0xff800000
	s_waitcnt lgkmcnt(2)
	v_mfma_f32_32x32x16_bf16 v[64:79], v[8:11], v[100:103], v[64:79]
	s_waitcnt lgkmcnt(1)
	v_mfma_f32_32x32x16_bf16 v[64:79], v[4:7], v[104:107], v[64:79]
	ds_read_b128 v[4:7], v123 offset:96
	s_waitcnt lgkmcnt(0)
	v_mfma_f32_32x32x16_bf16 v[64:79], v[4:7], v[108:111], v[64:79]
	ds_read_b128 v[4:7], v123 offset:4608
	s_waitcnt lgkmcnt(0)
	v_mfma_f32_32x32x16_bf16 v[48:63], v[4:7], v[0:3], 0
	ds_read_b128 v[4:7], v123 offset:4640
	s_waitcnt lgkmcnt(0)
	v_mfma_f32_32x32x16_bf16 v[48:63], v[4:7], v[100:103], v[48:63]
	ds_read_b128 v[4:7], v123 offset:4672
	s_waitcnt lgkmcnt(0)
	v_mfma_f32_32x32x16_bf16 v[48:63], v[4:7], v[104:107], v[48:63]
	ds_read_b128 v[4:7], v123 offset:4704
	s_waitcnt lgkmcnt(0)
	v_mfma_f32_32x32x16_bf16 v[48:63], v[4:7], v[108:111], v[48:63]
	ds_read_b128 v[4:7], v123 offset:9216
	s_waitcnt lgkmcnt(0)
	v_mfma_f32_32x32x16_bf16 v[32:47], v[4:7], v[0:3], 0
	ds_read_b128 v[4:7], v123 offset:9248
	s_waitcnt lgkmcnt(0)
	v_mfma_f32_32x32x16_bf16 v[32:47], v[4:7], v[100:103], v[32:47]
	ds_read_b128 v[4:7], v123 offset:9280
	s_waitcnt lgkmcnt(0)
	v_mfma_f32_32x32x16_bf16 v[32:47], v[4:7], v[104:107], v[32:47]
	ds_read_b128 v[4:7], v123 offset:9312
	s_waitcnt lgkmcnt(0)
	v_mfma_f32_32x32x16_bf16 v[32:47], v[4:7], v[108:111], v[32:47]
	ds_read_b128 v[4:7], v123 offset:13824
	s_waitcnt lgkmcnt(0)
	v_mfma_f32_32x32x16_bf16 v[16:31], v[4:7], v[0:3], 0
	ds_read_b128 v[4:7], v123 offset:13856
	s_waitcnt lgkmcnt(0)
	v_mfma_f32_32x32x16_bf16 v[16:31], v[4:7], v[100:103], v[16:31]
	ds_read_b128 v[4:7], v123 offset:13888
	s_waitcnt lgkmcnt(0)
	v_mfma_f32_32x32x16_bf16 v[16:31], v[4:7], v[104:107], v[16:31]
	ds_read_b128 v[4:7], v123 offset:13920
	s_waitcnt lgkmcnt(0)
	v_mfma_f32_32x32x16_bf16 v[16:31], v[4:7], v[108:111], v[16:31]
	ds_read_b128 v[4:7], v123 offset:18432
	s_waitcnt lgkmcnt(0)
	v_mfma_f32_32x32x16_bf16 v[0:15], v[4:7], v[0:3], 0
	v_mfma_f32_32x32x16_bf16 v[0:15], v[158:161], v[100:103], v[0:15]
	ds_read_b128 v[100:103], v123 offset:18496
	s_waitcnt lgkmcnt(0)
	v_mfma_f32_32x32x16_bf16 v[0:15], v[100:103], v[104:107], v[0:15]
	ds_read_b128 v[100:103], v123 offset:18528
	s_waitcnt lgkmcnt(0)
	v_mfma_f32_32x32x16_bf16 v[0:15], v[100:103], v[108:111], v[0:15]
	v_lshlrev_b32_e32 v108, 2, v157
	v_lshl_add_u32 v100, v116, 2, s85
	v_add_u32_e32 v101, v149, v108
	ds_read_b32 v100, v100 offset:512
	ds_read_b128 v[102:105], v101
	v_mov_b32_e32 v116, v64
	v_add_u32_e32 v110, s85, v108
	v_add_u32_e32 v111, v153, v108
	s_waitcnt lgkmcnt(0)
	v_sub_u32_e32 v102, v100, v102
	v_cvt_f32_i32_e32 v102, v102
	v_and_b32_e32 v169, 0x7fffffff, v102
	v_sub_u32_e32 v102, v100, v103
	v_cvt_f32_i32_e32 v102, v102
	v_pk_mul_f32 v[106:107], v[116:117], v[168:169]
	v_mov_b32_e32 v116, v65
	v_sub_f32_e32 v64, v106, v107
	v_and_b32_e32 v169, 0x7fffffff, v102
	v_pk_mul_f32 v[102:103], v[116:117], v[168:169]
	v_mov_b32_e32 v116, v66
	v_sub_f32_e32 v65, v102, v103
	v_sub_u32_e32 v102, v100, v104
	v_cvt_f32_i32_e32 v102, v102
	v_cndmask_b32_e64 v64, v215, v64, s[10:11]
	v_cndmask_b32_e64 v65, v215, v65, s[12:13]
	v_max3_f32 v106, v64, s96, v65
	v_and_b32_e32 v169, 0x7fffffff, v102
	v_pk_mul_f32 v[102:103], v[116:117], v[168:169]
	v_mov_b32_e32 v116, v67
	v_sub_f32_e32 v66, v102, v103
	v_sub_u32_e32 v102, v100, v105
	v_cvt_f32_i32_e32 v102, v102
	v_cndmask_b32_e64 v66, v215, v66, s[16:17]
	s_movk_i32 s96, 0x60
	v_cmp_eq_u32_e32 vcc, s96, v157
	v_and_b32_e32 v169, 0x7fffffff, v102
	v_pk_mul_f32 v[102:103], v[116:117], v[168:169]
	v_mov_b32_e32 v116, v68
	v_sub_f32_e32 v67, v102, v103
	v_lshl_add_u32 v102, v150, 2, v110
	ds_read_b128 v[102:105], v102
	v_cndmask_b32_e64 v67, v215, v67, s[20:21]
	v_max3_f32 v109, v106, v66, v67
	s_or_b64 vcc, s[6:7], vcc
	s_mov_b32 s96, 32
	s_waitcnt lgkmcnt(0)
	v_sub_u32_e32 v102, v100, v102
	v_cvt_f32_i32_e32 v102, v102
	v_and_b32_e32 v169, 0x7fffffff, v102
	v_sub_u32_e32 v102, v100, v103
	v_cvt_f32_i32_e32 v102, v102
	v_pk_mul_f32 v[106:107], v[116:117], v[168:169]
	v_mov_b32_e32 v116, v69
	v_sub_f32_e32 v68, v106, v107
	v_and_b32_e32 v169, 0x7fffffff, v102
	v_pk_mul_f32 v[102:103], v[116:117], v[168:169]
	v_mov_b32_e32 v116, v70
	v_sub_f32_e32 v69, v102, v103
	v_sub_u32_e32 v102, v100, v104
	v_cvt_f32_i32_e32 v102, v102
	v_cndmask_b32_e64 v68, v215, v68, s[24:25]
	v_cndmask_b32_e64 v69, v215, v69, s[28:29]
	v_max3_f32 v106, v109, v68, v69
	v_and_b32_e32 v169, 0x7fffffff, v102
	v_pk_mul_f32 v[102:103], v[116:117], v[168:169]
	v_mov_b32_e32 v116, v71
	v_sub_f32_e32 v70, v102, v103
	v_sub_u32_e32 v102, v100, v105
	v_cvt_f32_i32_e32 v102, v102
	v_cndmask_b32_e64 v70, v215, v70, s[34:35]
	v_and_b32_e32 v169, 0x7fffffff, v102
	v_pk_mul_f32 v[102:103], v[116:117], v[168:169]
	v_mov_b32_e32 v116, v72
	v_sub_f32_e32 v71, v102, v103
	v_lshl_add_u32 v102, v152, 2, v110
	ds_read_b128 v[102:105], v102
	v_cndmask_b32_e64 v71, v215, v71, s[38:39]
	v_max3_f32 v109, v106, v70, v71
	s_waitcnt lgkmcnt(0)
	v_sub_u32_e32 v102, v100, v102
	v_cvt_f32_i32_e32 v102, v102
	v_and_b32_e32 v169, 0x7fffffff, v102
	v_sub_u32_e32 v102, v100, v103
	v_cvt_f32_i32_e32 v102, v102
	v_pk_mul_f32 v[106:107], v[116:117], v[168:169]
	v_mov_b32_e32 v116, v73
	v_sub_f32_e32 v72, v106, v107
	v_and_b32_e32 v169, 0x7fffffff, v102
	v_pk_mul_f32 v[102:103], v[116:117], v[168:169]
	v_mov_b32_e32 v116, v74
	v_sub_f32_e32 v73, v102, v103
	v_sub_u32_e32 v102, v100, v104
	v_cvt_f32_i32_e32 v102, v102
	v_cndmask_b32_e64 v72, v215, v72, s[42:43]
	v_cndmask_b32_e64 v73, v215, v73, s[46:47]
	v_max3_f32 v106, v109, v72, v73
	v_and_b32_e32 v169, 0x7fffffff, v102
	v_pk_mul_f32 v[102:103], v[116:117], v[168:169]
	v_mov_b32_e32 v116, v75
	v_sub_f32_e32 v74, v102, v103
	v_sub_u32_e32 v102, v100, v105
	v_cvt_f32_i32_e32 v102, v102
	v_cndmask_b32_e64 v74, v215, v74, s[50:51]
	v_and_b32_e32 v169, 0x7fffffff, v102
	v_pk_mul_f32 v[102:103], v[116:117], v[168:169]
	v_mov_b32_e32 v116, v76
	v_sub_f32_e32 v75, v102, v103
	v_lshl_add_u32 v102, v154, 2, v110
	ds_read_b128 v[102:105], v102
	v_cndmask_b32_e64 v75, v215, v75, s[54:55]
	v_max3_f32 v109, v106, v74, v75
	v_add_u32_e32 v110, v151, v108
	v_add_u32_e32 v108, v155, v108
	s_waitcnt lgkmcnt(0)
	v_sub_u32_e32 v102, v100, v102
	v_cvt_f32_i32_e32 v102, v102
	v_and_b32_e32 v169, 0x7fffffff, v102
	v_sub_u32_e32 v102, v100, v103
	v_cvt_f32_i32_e32 v102, v102
	v_pk_mul_f32 v[106:107], v[116:117], v[168:169]
	v_mov_b32_e32 v116, v77
	v_sub_f32_e32 v76, v106, v107
	v_and_b32_e32 v169, 0x7fffffff, v102
	v_pk_mul_f32 v[102:103], v[116:117], v[168:169]
	v_mov_b32_e32 v116, v78
	v_sub_f32_e32 v77, v102, v103
	v_sub_u32_e32 v102, v100, v104
	v_cvt_f32_i32_e32 v102, v102
	v_cndmask_b32_e64 v76, v215, v76, s[58:59]
	v_cndmask_b32_e64 v77, v215, v77, s[62:63]
	v_max3_f32 v106, v109, v76, v77
	v_and_b32_e32 v169, 0x7fffffff, v102
	v_pk_mul_f32 v[102:103], v[116:117], v[168:169]
	v_mov_b32_e32 v116, v79
	v_sub_f32_e32 v78, v102, v103
	v_sub_u32_e32 v102, v100, v105
	v_cvt_f32_i32_e32 v102, v102
	v_cndmask_b32_e64 v78, v215, v78, s[66:67]
	v_and_b32_e32 v169, 0x7fffffff, v102
	v_pk_mul_f32 v[102:103], v[116:117], v[168:169]
	v_mov_b32_e32 v116, v48
	v_sub_f32_e32 v79, v102, v103
	ds_read_b128 v[102:105], v101 offset:128
	v_cndmask_b32_e64 v79, v215, v79, s[70:71]
	v_max3_f32 v109, v106, v78, v79
	s_waitcnt lgkmcnt(0)
	v_sub_u32_e32 v102, v100, v102
	v_cvt_f32_i32_e32 v102, v102
	v_and_b32_e32 v169, 0x7fffffff, v102
	v_sub_u32_e32 v102, v100, v103
	v_cvt_f32_i32_e32 v102, v102
	v_pk_mul_f32 v[106:107], v[116:117], v[168:169]
	v_mov_b32_e32 v116, v49
	v_sub_f32_e32 v48, v106, v107
	v_and_b32_e32 v169, 0x7fffffff, v102
	v_pk_mul_f32 v[102:103], v[116:117], v[168:169]
	v_mov_b32_e32 v116, v50
	v_sub_f32_e32 v49, v102, v103
	v_sub_u32_e32 v102, v100, v104
	v_cvt_f32_i32_e32 v102, v102
	v_cndmask_b32_e32 v48, v215, v48, vcc
	v_cndmask_b32_e32 v49, v215, v49, vcc
	v_max3_f32 v106, v109, v48, v49
	v_and_b32_e32 v169, 0x7fffffff, v102
	v_pk_mul_f32 v[102:103], v[116:117], v[168:169]
	v_mov_b32_e32 v116, v51
	v_sub_f32_e32 v50, v102, v103
	v_sub_u32_e32 v102, v100, v105
	v_cvt_f32_i32_e32 v102, v102
	v_cndmask_b32_e32 v50, v215, v50, vcc
	v_and_b32_e32 v169, 0x7fffffff, v102
	v_pk_mul_f32 v[102:103], v[116:117], v[168:169]
	v_mov_b32_e32 v116, v52
	v_sub_f32_e32 v51, v102, v103
	ds_read_b128 v[102:105], v110 offset:128
	v_cndmask_b32_e32 v51, v215, v51, vcc
	v_max3_f32 v109, v106, v50, v51
	s_waitcnt lgkmcnt(0)
	v_sub_u32_e32 v102, v100, v102
	v_cvt_f32_i32_e32 v102, v102
	v_and_b32_e32 v169, 0x7fffffff, v102
	v_sub_u32_e32 v102, v100, v103
	v_cvt_f32_i32_e32 v102, v102
	v_pk_mul_f32 v[106:107], v[116:117], v[168:169]
	v_mov_b32_e32 v116, v53
	v_sub_f32_e32 v52, v106, v107
	v_and_b32_e32 v169, 0x7fffffff, v102
	v_pk_mul_f32 v[102:103], v[116:117], v[168:169]
	v_mov_b32_e32 v116, v54
	v_sub_f32_e32 v53, v102, v103
	v_sub_u32_e32 v102, v100, v104
	v_cvt_f32_i32_e32 v102, v102
	v_cndmask_b32_e32 v52, v215, v52, vcc
	v_cndmask_b32_e32 v53, v215, v53, vcc
	v_max3_f32 v106, v109, v52, v53
	v_and_b32_e32 v169, 0x7fffffff, v102
	v_pk_mul_f32 v[102:103], v[116:117], v[168:169]
	v_mov_b32_e32 v116, v55
	v_sub_f32_e32 v54, v102, v103
	v_sub_u32_e32 v102, v100, v105
	v_cvt_f32_i32_e32 v102, v102
	v_cndmask_b32_e32 v54, v215, v54, vcc
	v_and_b32_e32 v169, 0x7fffffff, v102
	v_pk_mul_f32 v[102:103], v[116:117], v[168:169]
	v_mov_b32_e32 v116, v56
	v_sub_f32_e32 v55, v102, v103
	ds_read_b128 v[102:105], v111 offset:128
	v_cndmask_b32_e32 v55, v215, v55, vcc
	v_max3_f32 v109, v106, v54, v55
	s_waitcnt lgkmcnt(0)
	v_sub_u32_e32 v102, v100, v102
	v_cvt_f32_i32_e32 v102, v102
	v_and_b32_e32 v169, 0x7fffffff, v102
	v_sub_u32_e32 v102, v100, v103
	v_cvt_f32_i32_e32 v102, v102
	v_pk_mul_f32 v[106:107], v[116:117], v[168:169]
	v_mov_b32_e32 v116, v57
	v_sub_f32_e32 v56, v106, v107
	v_and_b32_e32 v169, 0x7fffffff, v102
	v_pk_mul_f32 v[102:103], v[116:117], v[168:169]
	v_mov_b32_e32 v116, v58
	v_sub_f32_e32 v57, v102, v103
	v_sub_u32_e32 v102, v100, v104
	v_cvt_f32_i32_e32 v102, v102
	v_cndmask_b32_e32 v56, v215, v56, vcc
	v_cndmask_b32_e32 v57, v215, v57, vcc
	v_max3_f32 v106, v109, v56, v57
	v_and_b32_e32 v169, 0x7fffffff, v102
	v_pk_mul_f32 v[102:103], v[116:117], v[168:169]
	v_mov_b32_e32 v116, v59
	v_sub_f32_e32 v58, v102, v103
	v_sub_u32_e32 v102, v100, v105
	v_cvt_f32_i32_e32 v102, v102
	v_cndmask_b32_e32 v58, v215, v58, vcc
	v_and_b32_e32 v169, 0x7fffffff, v102
	v_pk_mul_f32 v[102:103], v[116:117], v[168:169]
	v_mov_b32_e32 v116, v60
	v_sub_f32_e32 v59, v102, v103
	ds_read_b128 v[102:105], v108 offset:128
	v_cndmask_b32_e32 v59, v215, v59, vcc
	v_max3_f32 v109, v106, v58, v59
	s_waitcnt lgkmcnt(0)
	v_sub_u32_e32 v102, v100, v102
	v_cvt_f32_i32_e32 v102, v102
	v_and_b32_e32 v169, 0x7fffffff, v102
	v_sub_u32_e32 v102, v100, v103
	v_cvt_f32_i32_e32 v102, v102
	v_pk_mul_f32 v[106:107], v[116:117], v[168:169]
	v_mov_b32_e32 v116, v61
	v_sub_f32_e32 v60, v106, v107
	v_and_b32_e32 v169, 0x7fffffff, v102
	v_pk_mul_f32 v[102:103], v[116:117], v[168:169]
	v_mov_b32_e32 v116, v62
	v_sub_f32_e32 v61, v102, v103
	v_sub_u32_e32 v102, v100, v104
	v_cvt_f32_i32_e32 v102, v102
	v_cndmask_b32_e32 v60, v215, v60, vcc
	v_cndmask_b32_e32 v61, v215, v61, vcc
	v_max3_f32 v106, v109, v60, v61
	v_and_b32_e32 v169, 0x7fffffff, v102
	v_pk_mul_f32 v[102:103], v[116:117], v[168:169]
	v_mov_b32_e32 v116, v63
	v_sub_f32_e32 v62, v102, v103
	v_cndmask_b32_e32 v107, v215, v62, vcc
	v_sub_u32_e32 v62, v100, v105
	v_cvt_f32_i32_e32 v62, v62
	ds_read_b128 v[102:105], v101 offset:256
	v_and_b32_e32 v169, 0x7fffffff, v62
	v_pk_mul_f32 v[62:63], v[116:117], v[168:169]
	v_mov_b32_e32 v116, v32
	v_sub_f32_e32 v62, v62, v63
	v_cndmask_b32_e32 v109, v215, v62, vcc
	s_waitcnt lgkmcnt(0)
	v_sub_u32_e32 v62, v100, v102
	v_cvt_f32_i32_e32 v62, v62
	v_max3_f32 v106, v106, v107, v109
	v_and_b32_e32 v169, 0x7fffffff, v62
	v_pk_mul_f32 v[62:63], v[116:117], v[168:169]
	v_mov_b32_e32 v116, v33
	v_sub_f32_e32 v32, v62, v63
	v_cndmask_b32_e64 v102, v32, v215, s[74:75]
	v_sub_u32_e32 v32, v100, v103
	v_cvt_f32_i32_e32 v32, v32
	v_and_b32_e32 v169, 0x7fffffff, v32
	v_pk_mul_f32 v[32:33], v[116:117], v[168:169]
	v_mov_b32_e32 v116, v34
	v_sub_f32_e32 v32, v32, v33
	v_cndmask_b32_e64 v103, v32, v215, s[74:75]
	v_sub_u32_e32 v32, v100, v104
	v_cvt_f32_i32_e32 v32, v32
	v_max3_f32 v62, v106, v102, v103
	v_and_b32_e32 v169, 0x7fffffff, v32
	v_pk_mul_f32 v[32:33], v[116:117], v[168:169]
	v_mov_b32_e32 v116, v35
	v_sub_f32_e32 v32, v32, v33
	v_cndmask_b32_e64 v104, v32, v215, s[74:75]
	v_sub_u32_e32 v32, v100, v105
	v_cvt_f32_i32_e32 v32, v32
	v_and_b32_e32 v169, 0x7fffffff, v32
	v_pk_mul_f32 v[32:33], v[116:117], v[168:169]
	v_mov_b32_e32 v116, v36
	v_sub_f32_e32 v32, v32, v33
	v_cndmask_b32_e64 v105, v32, v215, s[74:75]
	ds_read_b128 v[32:35], v110 offset:256
	v_max3_f32 v106, v62, v104, v105
	s_waitcnt lgkmcnt(0)
	v_sub_u32_e32 v32, v100, v32
	v_cvt_f32_i32_e32 v32, v32
	v_and_b32_e32 v169, 0x7fffffff, v32
	v_pk_mul_f32 v[62:63], v[116:117], v[168:169]
	v_mov_b32_e32 v116, v37
	v_sub_f32_e32 v32, v62, v63
	v_cndmask_b32_e64 v62, v32, v215, s[74:75]
	v_sub_u32_e32 v32, v100, v33
	v_cvt_f32_i32_e32 v32, v32
	v_and_b32_e32 v169, 0x7fffffff, v32
	v_pk_mul_f32 v[32:33], v[116:117], v[168:169]
	v_mov_b32_e32 v116, v38
	v_sub_f32_e32 v32, v32, v33
	v_cndmask_b32_e64 v63, v32, v215, s[74:75]
	v_sub_u32_e32 v32, v100, v34
	v_cvt_f32_i32_e32 v32, v32
	v_max3_f32 v36, v106, v62, v63
	v_and_b32_e32 v169, 0x7fffffff, v32
	v_pk_mul_f32 v[32:33], v[116:117], v[168:169]
	v_mov_b32_e32 v116, v39
	v_sub_f32_e32 v32, v32, v33
	v_cndmask_b32_e64 v106, v32, v215, s[74:75]
	v_sub_u32_e32 v32, v100, v35
	v_cvt_f32_i32_e32 v32, v32
	v_and_b32_e32 v169, 0x7fffffff, v32
	v_pk_mul_f32 v[32:33], v[116:117], v[168:169]
	v_mov_b32_e32 v116, v40
	v_sub_f32_e32 v32, v32, v33
	v_cndmask_b32_e64 v123, v32, v215, s[74:75]
	ds_read_b128 v[32:35], v111 offset:256
	v_max3_f32 v38, v36, v106, v123
	s_waitcnt lgkmcnt(0)
	v_sub_u32_e32 v32, v100, v32
	v_cvt_f32_i32_e32 v32, v32
	v_and_b32_e32 v169, 0x7fffffff, v32
	v_pk_mul_f32 v[36:37], v[116:117], v[168:169]
	v_mov_b32_e32 v116, v41
	v_sub_f32_e32 v32, v36, v37
	v_cndmask_b32_e64 v125, v32, v215, s[74:75]
	v_sub_u32_e32 v32, v100, v33
	v_cvt_f32_i32_e32 v32, v32
	v_and_b32_e32 v169, 0x7fffffff, v32
	v_pk_mul_f32 v[32:33], v[116:117], v[168:169]
	v_mov_b32_e32 v116, v42
	v_sub_f32_e32 v32, v32, v33
	v_cndmask_b32_e64 v158, v32, v215, s[74:75]
	v_sub_u32_e32 v32, v100, v34
	v_cvt_f32_i32_e32 v32, v32
	v_max3_f32 v36, v38, v125, v158
	v_and_b32_e32 v169, 0x7fffffff, v32
	v_pk_mul_f32 v[32:33], v[116:117], v[168:169]
	v_mov_b32_e32 v116, v43
	v_sub_f32_e32 v32, v32, v33
	v_cndmask_b32_e64 v159, v32, v215, s[74:75]
	v_sub_u32_e32 v32, v100, v35
	v_cvt_f32_i32_e32 v32, v32
	v_and_b32_e32 v169, 0x7fffffff, v32
	v_pk_mul_f32 v[32:33], v[116:117], v[168:169]
	v_mov_b32_e32 v116, v44
	v_sub_f32_e32 v32, v32, v33
	v_cndmask_b32_e64 v160, v32, v215, s[74:75]
	ds_read_b128 v[32:35], v108 offset:256
	v_max3_f32 v38, v36, v159, v160
	s_waitcnt lgkmcnt(0)
	v_sub_u32_e32 v32, v100, v32
	v_cvt_f32_i32_e32 v32, v32
	v_and_b32_e32 v169, 0x7fffffff, v32
	v_pk_mul_f32 v[36:37], v[116:117], v[168:169]
	v_mov_b32_e32 v116, v45
	v_sub_f32_e32 v32, v36, v37
	v_cndmask_b32_e64 v44, v32, v215, s[74:75]
	v_sub_u32_e32 v32, v100, v33
	v_cvt_f32_i32_e32 v32, v32
	v_and_b32_e32 v169, 0x7fffffff, v32
	v_pk_mul_f32 v[32:33], v[116:117], v[168:169]
	v_mov_b32_e32 v116, v46
	v_sub_f32_e32 v32, v32, v33
	v_cndmask_b32_e64 v45, v32, v215, s[74:75]
	v_sub_u32_e32 v32, v100, v34
	v_cvt_f32_i32_e32 v32, v32
	v_max3_f32 v36, v38, v44, v45
	v_and_b32_e32 v169, 0x7fffffff, v32
	v_pk_mul_f32 v[32:33], v[116:117], v[168:169]
	v_mov_b32_e32 v116, v47
	v_sub_f32_e32 v32, v32, v33
	v_cndmask_b32_e64 v46, v32, v215, s[74:75]
	v_sub_u32_e32 v32, v100, v35
	v_cvt_f32_i32_e32 v32, v32
	v_and_b32_e32 v169, 0x7fffffff, v32
	v_pk_mul_f32 v[32:33], v[116:117], v[168:169]
	v_mov_b32_e32 v116, v16
	v_sub_f32_e32 v32, v32, v33
	v_cndmask_b32_e64 v47, v32, v215, s[74:75]
	ds_read_b128 v[32:35], v101 offset:384
	v_max3_f32 v38, v36, v46, v47
	v_or_b32_e32 v36, s76, v157
	v_cmp_eq_u32_e32 vcc, 0, v36
	s_waitcnt lgkmcnt(0)
	v_sub_u32_e32 v32, v100, v32
	v_cvt_f32_i32_e32 v32, v32
	v_and_b32_e32 v169, 0x7fffffff, v32
	v_pk_mul_f32 v[36:37], v[116:117], v[168:169]
	v_mov_b32_e32 v116, v17
	v_sub_f32_e32 v16, v36, v37
	v_cndmask_b32_e32 v161, v16, v215, vcc
	v_sub_u32_e32 v16, v100, v33
	v_cvt_f32_i32_e32 v16, v16
	v_and_b32_e32 v169, 0x7fffffff, v16
	v_pk_mul_f32 v[16:17], v[116:117], v[168:169]
	v_mov_b32_e32 v116, v18
	v_sub_f32_e32 v16, v16, v17
	v_cndmask_b32_e32 v162, v16, v215, vcc
	v_sub_u32_e32 v16, v100, v34
	v_cvt_f32_i32_e32 v16, v16
	v_max3_f32 v32, v38, v161, v162
	v_and_b32_e32 v169, 0x7fffffff, v16
	v_pk_mul_f32 v[16:17], v[116:117], v[168:169]
	v_mov_b32_e32 v116, v19
	v_sub_f32_e32 v16, v16, v17
	v_cndmask_b32_e32 v163, v16, v215, vcc
	v_sub_u32_e32 v16, v100, v35
	v_cvt_f32_i32_e32 v16, v16
	v_and_b32_e32 v169, 0x7fffffff, v16
	v_pk_mul_f32 v[16:17], v[116:117], v[168:169]
	v_mov_b32_e32 v116, v20
	v_sub_f32_e32 v16, v16, v17
	v_cndmask_b32_e32 v164, v16, v215, vcc
	ds_read_b128 v[16:19], v110 offset:384
	v_max3_f32 v34, v32, v163, v164
	s_waitcnt lgkmcnt(0)
	v_sub_u32_e32 v16, v100, v16
	v_cvt_f32_i32_e32 v16, v16
	v_and_b32_e32 v169, 0x7fffffff, v16
	v_pk_mul_f32 v[32:33], v[116:117], v[168:169]
	v_mov_b32_e32 v116, v21
	v_sub_f32_e32 v16, v32, v33
	v_cndmask_b32_e32 v165, v16, v215, vcc
	v_sub_u32_e32 v16, v100, v17
	v_cvt_f32_i32_e32 v16, v16
	v_and_b32_e32 v169, 0x7fffffff, v16
	v_pk_mul_f32 v[16:17], v[116:117], v[168:169]
	v_mov_b32_e32 v116, v22
	v_sub_f32_e32 v16, v16, v17
	v_cndmask_b32_e32 v166, v16, v215, vcc
	v_sub_u32_e32 v16, v100, v18
	v_cvt_f32_i32_e32 v16, v16
	v_max3_f32 v20, v34, v165, v166
	v_and_b32_e32 v169, 0x7fffffff, v16
	v_pk_mul_f32 v[16:17], v[116:117], v[168:169]
	v_mov_b32_e32 v116, v23
	v_sub_f32_e32 v16, v16, v17
	v_cndmask_b32_e32 v22, v16, v215, vcc
	v_sub_u32_e32 v16, v100, v19
	v_cvt_f32_i32_e32 v16, v16
	v_and_b32_e32 v169, 0x7fffffff, v16
	v_pk_mul_f32 v[16:17], v[116:117], v[168:169]
	v_mov_b32_e32 v116, v24
	v_sub_f32_e32 v16, v16, v17
	v_cndmask_b32_e32 v23, v16, v215, vcc
	ds_read_b128 v[16:19], v111 offset:384
	v_max3_f32 v32, v20, v22, v23
	s_waitcnt lgkmcnt(0)
	v_sub_u32_e32 v16, v100, v16
	v_cvt_f32_i32_e32 v16, v16
	v_and_b32_e32 v169, 0x7fffffff, v16
	v_pk_mul_f32 v[20:21], v[116:117], v[168:169]
	v_mov_b32_e32 v116, v25
	v_sub_f32_e32 v16, v20, v21
	v_cndmask_b32_e32 v24, v16, v215, vcc
	v_sub_u32_e32 v16, v100, v17
	v_cvt_f32_i32_e32 v16, v16
	v_and_b32_e32 v169, 0x7fffffff, v16
	v_pk_mul_f32 v[16:17], v[116:117], v[168:169]
	v_mov_b32_e32 v116, v26
	v_sub_f32_e32 v16, v16, v17
	v_cndmask_b32_e32 v25, v16, v215, vcc
	v_sub_u32_e32 v16, v100, v18
	v_cvt_f32_i32_e32 v16, v16
	v_max3_f32 v20, v32, v24, v25
	v_and_b32_e32 v169, 0x7fffffff, v16
	v_pk_mul_f32 v[16:17], v[116:117], v[168:169]
	v_mov_b32_e32 v116, v27
	v_sub_f32_e32 v16, v16, v17
	v_cndmask_b32_e32 v26, v16, v215, vcc
	v_sub_u32_e32 v16, v100, v19
	v_cvt_f32_i32_e32 v16, v16
	v_and_b32_e32 v169, 0x7fffffff, v16
	v_pk_mul_f32 v[16:17], v[116:117], v[168:169]
	v_mov_b32_e32 v116, v28
	v_sub_f32_e32 v16, v16, v17
	v_cndmask_b32_e32 v27, v16, v215, vcc
	ds_read_b128 v[16:19], v108 offset:384
	v_max3_f32 v32, v20, v26, v27
	s_waitcnt lgkmcnt(0)
	v_sub_u32_e32 v16, v100, v16
	v_cvt_f32_i32_e32 v16, v16
	v_and_b32_e32 v169, 0x7fffffff, v16
	v_pk_mul_f32 v[20:21], v[116:117], v[168:169]
	v_mov_b32_e32 v116, v29
	v_sub_f32_e32 v16, v20, v21
	v_cndmask_b32_e32 v28, v16, v215, vcc
	v_sub_u32_e32 v16, v100, v17
	v_cvt_f32_i32_e32 v16, v16
	v_and_b32_e32 v169, 0x7fffffff, v16
	v_pk_mul_f32 v[16:17], v[116:117], v[168:169]
	v_mov_b32_e32 v116, v30
	v_sub_f32_e32 v16, v16, v17
	v_cndmask_b32_e32 v29, v16, v215, vcc
	v_sub_u32_e32 v16, v100, v18
	v_cvt_f32_i32_e32 v16, v16
	v_max3_f32 v20, v32, v28, v29
	v_and_b32_e32 v169, 0x7fffffff, v16
	v_pk_mul_f32 v[16:17], v[116:117], v[168:169]
	v_mov_b32_e32 v116, v31
	v_sub_f32_e32 v16, v16, v17
	v_cndmask_b32_e32 v30, v16, v215, vcc
	v_sub_u32_e32 v16, v100, v19
	v_cvt_f32_i32_e32 v16, v16
	v_and_b32_e32 v169, 0x7fffffff, v16
	v_pk_mul_f32 v[16:17], v[116:117], v[168:169]
	v_mov_b32_e32 v116, v0
	v_sub_f32_e32 v16, v16, v17
	v_cndmask_b32_e32 v31, v16, v215, vcc
	ds_read_b128 v[16:19], v101 offset:512
	v_max3_f32 v32, v20, v30, v31
	s_and_b64 vcc, exec, s[82:83]
	s_mov_b64 s[82:83], 0
	s_waitcnt lgkmcnt(0)
	v_sub_u32_e32 v16, v100, v16
	v_cvt_f32_i32_e32 v16, v16
	v_and_b32_e32 v169, 0x7fffffff, v16
	v_pk_mul_f32 v[20:21], v[116:117], v[168:169]
	v_mov_b32_e32 v116, v1
	v_sub_f32_e32 v0, v20, v21
	v_cndmask_b32_e64 v20, v0, v215, s[8:9]
	v_sub_u32_e32 v0, v100, v17
	v_cvt_f32_i32_e32 v0, v0
	v_and_b32_e32 v169, 0x7fffffff, v0
	v_pk_mul_f32 v[0:1], v[116:117], v[168:169]
	v_mov_b32_e32 v116, v2
	v_sub_f32_e32 v0, v0, v1
	v_cndmask_b32_e64 v21, v215, v0, s[72:73]
	v_sub_u32_e32 v0, v100, v18
	v_cvt_f32_i32_e32 v0, v0
	v_max3_f32 v16, v32, v20, v21
	v_and_b32_e32 v169, 0x7fffffff, v0
	v_pk_mul_f32 v[0:1], v[116:117], v[168:169]
	v_mov_b32_e32 v116, v3
	v_sub_f32_e32 v0, v0, v1
	v_cndmask_b32_e64 v18, v0, v215, s[14:15]
	v_sub_u32_e32 v0, v100, v19
	v_cvt_f32_i32_e32 v0, v0
	v_and_b32_e32 v169, 0x7fffffff, v0
	v_pk_mul_f32 v[0:1], v[116:117], v[168:169]
	v_mov_b32_e32 v116, v4
	v_sub_f32_e32 v0, v0, v1
	v_cndmask_b32_e64 v19, v0, v215, s[18:19]
	ds_read_b128 v[0:3], v110 offset:512
	v_max3_f32 v32, v16, v18, v19
	s_waitcnt lgkmcnt(0)
	v_sub_u32_e32 v0, v100, v0
	v_cvt_f32_i32_e32 v0, v0
	v_and_b32_e32 v169, 0x7fffffff, v0
	v_pk_mul_f32 v[16:17], v[116:117], v[168:169]
	v_mov_b32_e32 v116, v5
	v_sub_f32_e32 v0, v16, v17
	v_cndmask_b32_e64 v16, v0, v215, s[22:23]
	v_sub_u32_e32 v0, v100, v1
	v_cvt_f32_i32_e32 v0, v0
	v_and_b32_e32 v169, 0x7fffffff, v0
	v_pk_mul_f32 v[0:1], v[116:117], v[168:169]
	v_mov_b32_e32 v116, v6
	v_sub_f32_e32 v0, v0, v1
	v_cndmask_b32_e64 v17, v0, v215, s[26:27]
	v_sub_u32_e32 v0, v100, v2
	v_cvt_f32_i32_e32 v0, v0
	v_max3_f32 v4, v32, v16, v17
	v_and_b32_e32 v169, 0x7fffffff, v0
	v_pk_mul_f32 v[0:1], v[116:117], v[168:169]
	v_mov_b32_e32 v116, v7
	v_sub_f32_e32 v0, v0, v1
	v_cndmask_b32_e64 v170, v0, v215, s[30:31]
	v_sub_u32_e32 v0, v100, v3
	v_cvt_f32_i32_e32 v0, v0
	v_and_b32_e32 v169, 0x7fffffff, v0
	v_pk_mul_f32 v[0:1], v[116:117], v[168:169]
	v_mov_b32_e32 v116, v8
	v_sub_f32_e32 v0, v0, v1
	v_cndmask_b32_e64 v171, v0, v215, s[36:37]
	ds_read_b128 v[0:3], v111 offset:512
	v_max3_f32 v6, v4, v170, v171
	s_waitcnt lgkmcnt(0)
	v_sub_u32_e32 v0, v100, v0
	v_cvt_f32_i32_e32 v0, v0
	v_and_b32_e32 v169, 0x7fffffff, v0
	v_pk_mul_f32 v[4:5], v[116:117], v[168:169]
	v_mov_b32_e32 v116, v9
	v_sub_f32_e32 v0, v4, v5
	v_cndmask_b32_e64 v172, v0, v215, s[40:41]
	v_sub_u32_e32 v0, v100, v1
	v_cvt_f32_i32_e32 v0, v0
	v_and_b32_e32 v169, 0x7fffffff, v0
	v_pk_mul_f32 v[0:1], v[116:117], v[168:169]
	v_mov_b32_e32 v116, v10
	v_sub_f32_e32 v0, v0, v1
	v_cndmask_b32_e64 v173, v0, v215, s[44:45]
	v_sub_u32_e32 v0, v100, v2
	v_cvt_f32_i32_e32 v0, v0
	v_max3_f32 v4, v6, v172, v173
	v_and_b32_e32 v169, 0x7fffffff, v0
	v_pk_mul_f32 v[0:1], v[116:117], v[168:169]
	v_mov_b32_e32 v116, v11
	v_sub_f32_e32 v0, v0, v1
	v_cndmask_b32_e64 v176, v0, v215, s[48:49]
	v_sub_u32_e32 v0, v100, v3
	v_cvt_f32_i32_e32 v0, v0
	v_and_b32_e32 v169, 0x7fffffff, v0
	v_pk_mul_f32 v[0:1], v[116:117], v[168:169]
	v_mov_b32_e32 v116, v12
	v_sub_f32_e32 v0, v0, v1
	v_cndmask_b32_e64 v177, v0, v215, s[52:53]
	ds_read_b128 v[0:3], v108 offset:512
	v_max3_f32 v6, v4, v176, v177
	s_waitcnt lgkmcnt(0)
	v_sub_u32_e32 v0, v100, v0
	v_cvt_f32_i32_e32 v0, v0
	v_and_b32_e32 v169, 0x7fffffff, v0
	v_pk_mul_f32 v[4:5], v[116:117], v[168:169]
	v_mov_b32_e32 v116, v13
	v_sub_f32_e32 v0, v4, v5
	v_cndmask_b32_e64 v178, v0, v215, s[56:57]
	v_sub_u32_e32 v0, v100, v1
	v_cvt_f32_i32_e32 v0, v0
	v_and_b32_e32 v169, 0x7fffffff, v0
	v_pk_mul_f32 v[0:1], v[116:117], v[168:169]
	v_mov_b32_e32 v116, v14
	v_sub_f32_e32 v0, v0, v1
	v_cndmask_b32_e64 v179, v0, v215, s[60:61]
	v_sub_u32_e32 v0, v100, v2
	v_cvt_f32_i32_e32 v0, v0
	v_max3_f32 v4, v6, v178, v179
	v_and_b32_e32 v169, 0x7fffffff, v0
	v_pk_mul_f32 v[0:1], v[116:117], v[168:169]
	v_mov_b32_e32 v116, v15
	v_sub_f32_e32 v0, v0, v1
	v_cndmask_b32_e64 v180, v0, v215, s[64:65]
	v_sub_u32_e32 v0, v100, v3
	v_cvt_f32_i32_e32 v0, v0
	v_and_b32_e32 v169, 0x7fffffff, v0
	v_pk_mul_f32 v[0:1], v[116:117], v[168:169]
	s_nop 0
	v_sub_f32_e32 v0, v0, v1
	v_cndmask_b32_e64 v116, v0, v215, s[68:69]
	v_max3_f32 v0, v4, v180, v116
	ds_bpermute_b32 v1, v144, v0
	s_waitcnt lgkmcnt(0)
	v_max3_f32 v169, v0, v1, v147
	v_sub_f32_e32 v0, v64, v169
	v_mul_f32_e32 v0, 0x3fb8aa3b, v0
	v_sub_f32_e32 v1, v65, v169
	v_exp_f32_e32 v0, v0
	v_mul_f32_e32 v1, 0x3fb8aa3b, v1
	v_exp_f32_e32 v1, v1
	v_sub_f32_e32 v45, v45, v169
	v_add_f32_e32 v2, 0, v0
	v_mul_f32_e32 v45, 0x3fb8aa3b, v45
	v_add_f32_e32 v3, v1, v2
	v_sub_f32_e32 v2, v66, v169
	v_mul_f32_e32 v2, 0x3fb8aa3b, v2
	v_exp_f32_e32 v2, v2
	v_sub_f32_e32 v44, v44, v169
	v_mul_f32_e32 v44, 0x3fb8aa3b, v44
	v_sub_f32_e32 v23, v23, v169
	v_add_f32_e32 v4, v2, v3
	v_sub_f32_e32 v3, v67, v169
	v_mul_f32_e32 v3, 0x3fb8aa3b, v3
	v_exp_f32_e32 v3, v3
	v_mul_f32_e32 v23, 0x3fb8aa3b, v23
	v_sub_f32_e32 v22, v22, v169
	v_mul_f32_e32 v22, 0x3fb8aa3b, v22
	v_add_f32_e32 v5, v3, v4
	v_sub_f32_e32 v4, v68, v169
	v_mul_f32_e32 v4, 0x3fb8aa3b, v4
	v_exp_f32_e32 v4, v4
	v_exp_f32_e32 v68, v44
	v_sub_f32_e32 v17, v17, v169
	v_mul_f32_e32 v17, 0x3fb8aa3b, v17
	v_add_f32_e32 v6, v4, v5
	v_sub_f32_e32 v5, v69, v169
	v_mul_f32_e32 v5, 0x3fb8aa3b, v5
	v_exp_f32_e32 v5, v5
	v_exp_f32_e32 v69, v45
	v_sub_f32_e32 v45, v46, v169
	v_mul_f32_e32 v45, 0x3fb8aa3b, v45
	v_add_f32_e32 v7, v5, v6
	v_sub_f32_e32 v6, v70, v169
	v_mul_f32_e32 v6, 0x3fb8aa3b, v6
	v_exp_f32_e32 v6, v6
	v_exp_f32_e32 v70, v45
	v_sub_f32_e32 v45, v47, v169
	v_mul_f32_e32 v45, 0x3fb8aa3b, v45
	v_add_f32_e32 v8, v6, v7
	v_sub_f32_e32 v7, v71, v169
	v_mul_f32_e32 v7, 0x3fb8aa3b, v7
	v_exp_f32_e32 v7, v7
	v_exp_f32_e32 v71, v45
	v_sub_f32_e32 v45, v161, v169
	v_mul_f32_e32 v45, 0x3fb8aa3b, v45
	v_add_f32_e32 v9, v7, v8
	v_sub_f32_e32 v8, v72, v169
	v_mul_f32_e32 v8, 0x3fb8aa3b, v8
	v_exp_f32_e32 v8, v8
	v_exp_f32_e32 v72, v45
	v_sub_f32_e32 v45, v162, v169
	v_mul_f32_e32 v45, 0x3fb8aa3b, v45
	v_add_f32_e32 v10, v8, v9
	v_sub_f32_e32 v9, v73, v169
	v_mul_f32_e32 v9, 0x3fb8aa3b, v9
	v_exp_f32_e32 v9, v9
	v_exp_f32_e32 v73, v45
	v_sub_f32_e32 v45, v163, v169
	v_mul_f32_e32 v45, 0x3fb8aa3b, v45
	v_add_f32_e32 v11, v9, v10
	v_sub_f32_e32 v10, v74, v169
	v_mul_f32_e32 v10, 0x3fb8aa3b, v10
	v_exp_f32_e32 v10, v10
	v_exp_f32_e32 v74, v45
	v_sub_f32_e32 v45, v164, v169
	v_mul_f32_e32 v45, 0x3fb8aa3b, v45
	v_add_f32_e32 v12, v10, v11
	v_sub_f32_e32 v11, v75, v169
	v_mul_f32_e32 v11, 0x3fb8aa3b, v11
	v_exp_f32_e32 v11, v11
	v_exp_f32_e32 v75, v45
	v_sub_f32_e32 v45, v165, v169
	v_mul_f32_e32 v45, 0x3fb8aa3b, v45
	v_add_f32_e32 v13, v11, v12
	v_sub_f32_e32 v12, v76, v169
	v_mul_f32_e32 v12, 0x3fb8aa3b, v12
	v_exp_f32_e32 v12, v12
	v_exp_f32_e32 v76, v45
	v_sub_f32_e32 v45, v166, v169
	v_mul_f32_e32 v45, 0x3fb8aa3b, v45
	v_add_f32_e32 v14, v12, v13
	v_sub_f32_e32 v13, v77, v169
	v_mul_f32_e32 v13, 0x3fb8aa3b, v13
	v_exp_f32_e32 v13, v13
	v_exp_f32_e32 v77, v45
	v_sub_f32_e32 v20, v20, v169
	v_mul_f32_e32 v20, 0x3fb8aa3b, v20
	v_add_f32_e32 v15, v13, v14
	v_sub_f32_e32 v14, v78, v169
	v_mul_f32_e32 v14, 0x3fb8aa3b, v14
	v_exp_f32_e32 v14, v14
	v_exp_f32_e32 v78, v22
	v_sub_f32_e32 v21, v21, v169
	v_exp_f32_e32 v108, v20
	v_add_f32_e32 v32, v14, v15
	v_sub_f32_e32 v15, v79, v169
	v_mul_f32_e32 v15, 0x3fb8aa3b, v15
	v_exp_f32_e32 v15, v15
	v_exp_f32_e32 v79, v23
	v_sub_f32_e32 v23, v24, v169
	v_mul_f32_e32 v23, 0x3fb8aa3b, v23
	v_add_f32_e32 v33, v15, v32
	v_sub_f32_e32 v32, v48, v169
	v_mul_f32_e32 v32, 0x3fb8aa3b, v32
	v_exp_f32_e32 v32, v32
	v_exp_f32_e32 v100, v23
	v_sub_f32_e32 v23, v25, v169
	v_mul_f32_e32 v23, 0x3fb8aa3b, v23
	v_add_f32_e32 v34, v32, v33
	v_sub_f32_e32 v33, v49, v169
	v_mul_f32_e32 v33, 0x3fb8aa3b, v33
	v_exp_f32_e32 v33, v33
	v_sub_f32_e32 v49, v60, v169
	v_mul_f32_e32 v49, 0x3fb8aa3b, v49
	v_exp_f32_e32 v101, v23
	v_add_f32_e32 v35, v33, v34
	v_sub_f32_e32 v34, v50, v169
	v_mul_f32_e32 v34, 0x3fb8aa3b, v34
	v_exp_f32_e32 v34, v34
	v_sub_f32_e32 v23, v26, v169
	v_mul_f32_e32 v23, 0x3fb8aa3b, v23
	v_mul_f32_e32 v21, 0x3fb8aa3b, v21
	v_add_f32_e32 v36, v34, v35
	v_sub_f32_e32 v35, v51, v169
	v_mul_f32_e32 v35, 0x3fb8aa3b, v35
	v_exp_f32_e32 v35, v35
	v_sub_f32_e32 v18, v18, v169
	v_mul_f32_e32 v18, 0x3fb8aa3b, v18
	v_sub_f32_e32 v19, v19, v169
	v_add_f32_e32 v37, v35, v36
	v_sub_f32_e32 v36, v52, v169
	v_mul_f32_e32 v36, 0x3fb8aa3b, v36
	v_exp_f32_e32 v36, v36
	v_exp_f32_e32 v52, v49
	v_sub_f32_e32 v49, v61, v169
	v_mul_f32_e32 v49, 0x3fb8aa3b, v49
	v_add_f32_e32 v38, v36, v37
	v_sub_f32_e32 v37, v53, v169
	v_mul_f32_e32 v37, 0x3fb8aa3b, v37
	v_exp_f32_e32 v37, v37
	v_exp_f32_e32 v53, v49
	v_sub_f32_e32 v49, v107, v169
	v_mul_f32_e32 v49, 0x3fb8aa3b, v49
	v_add_f32_e32 v39, v37, v38
	v_sub_f32_e32 v38, v54, v169
	v_mul_f32_e32 v38, 0x3fb8aa3b, v38
	v_exp_f32_e32 v38, v38
	v_exp_f32_e32 v54, v49
	v_sub_f32_e32 v49, v109, v169
	v_mul_f32_e32 v49, 0x3fb8aa3b, v49
	v_add_f32_e32 v40, v38, v39
	v_sub_f32_e32 v39, v55, v169
	v_mul_f32_e32 v39, 0x3fb8aa3b, v39
	v_exp_f32_e32 v39, v39
	v_exp_f32_e32 v55, v49
	v_sub_f32_e32 v49, v102, v169
	v_mul_f32_e32 v49, 0x3fb8aa3b, v49
	v_add_f32_e32 v41, v39, v40
	v_sub_f32_e32 v40, v56, v169
	v_mul_f32_e32 v40, 0x3fb8aa3b, v40
	v_exp_f32_e32 v40, v40
	v_exp_f32_e32 v56, v49
	v_sub_f32_e32 v49, v103, v169
	v_mul_f32_e32 v49, 0x3fb8aa3b, v49
	v_add_f32_e32 v42, v40, v41
	v_sub_f32_e32 v41, v57, v169
	v_mul_f32_e32 v41, 0x3fb8aa3b, v41
	v_exp_f32_e32 v41, v41
	v_exp_f32_e32 v57, v49
	v_sub_f32_e32 v49, v104, v169
	v_mul_f32_e32 v49, 0x3fb8aa3b, v49
	v_add_f32_e32 v43, v41, v42
	v_sub_f32_e32 v42, v58, v169
	v_mul_f32_e32 v42, 0x3fb8aa3b, v42
	v_exp_f32_e32 v42, v42
	v_exp_f32_e32 v58, v49
	v_sub_f32_e32 v49, v105, v169
	v_mul_f32_e32 v49, 0x3fb8aa3b, v49
	v_add_f32_e32 v48, v42, v43
	v_sub_f32_e32 v43, v59, v169
	v_mul_f32_e32 v43, 0x3fb8aa3b, v43
	v_exp_f32_e32 v43, v43
	v_exp_f32_e32 v59, v49
	v_sub_f32_e32 v49, v62, v169
	v_mul_f32_e32 v49, 0x3fb8aa3b, v49
	v_exp_f32_e32 v60, v49
	v_sub_f32_e32 v49, v63, v169
	v_mul_f32_e32 v49, 0x3fb8aa3b, v49
	v_add_f32_e32 v48, v43, v48
	v_exp_f32_e32 v61, v49
	v_sub_f32_e32 v49, v106, v169
	v_add_f32_e32 v48, v52, v48
	v_mul_f32_e32 v49, 0x3fb8aa3b, v49
	v_add_f32_e32 v48, v53, v48
	v_exp_f32_e32 v62, v49
	v_sub_f32_e32 v49, v123, v169
	v_add_f32_e32 v48, v54, v48
	v_mul_f32_e32 v49, 0x3fb8aa3b, v49
	v_add_f32_e32 v48, v55, v48
	v_exp_f32_e32 v63, v49
	v_sub_f32_e32 v49, v125, v169
	v_add_f32_e32 v48, v56, v48
	v_mul_f32_e32 v49, 0x3fb8aa3b, v49
	v_add_f32_e32 v48, v57, v48
	v_exp_f32_e32 v64, v49
	v_sub_f32_e32 v49, v158, v169
	v_add_f32_e32 v48, v58, v48
	v_mul_f32_e32 v49, 0x3fb8aa3b, v49
	v_add_f32_e32 v48, v59, v48
	v_exp_f32_e32 v65, v49
	v_sub_f32_e32 v49, v159, v169
	v_add_f32_e32 v48, v60, v48
	v_mul_f32_e32 v49, 0x3fb8aa3b, v49
	v_add_f32_e32 v48, v61, v48
	v_exp_f32_e32 v66, v49
	v_sub_f32_e32 v49, v160, v169
	v_add_f32_e32 v48, v62, v48
	v_mul_f32_e32 v49, 0x3fb8aa3b, v49
	v_add_f32_e32 v48, v63, v48
	v_exp_f32_e32 v67, v49
	v_add_f32_e32 v48, v64, v48
	v_add_f32_e32 v48, v65, v48
	v_add_f32_e32 v48, v66, v48
	v_add_f32_e32 v48, v67, v48
	v_add_f32_e32 v44, v68, v48
	v_add_f32_e32 v44, v69, v44
	v_add_f32_e32 v44, v70, v44
	v_add_f32_e32 v44, v71, v44
	v_add_f32_e32 v44, v72, v44
	v_add_f32_e32 v44, v73, v44
	v_exp_f32_e32 v102, v23
	v_sub_f32_e32 v23, v27, v169
	v_add_f32_e32 v44, v74, v44
	v_mul_f32_e32 v23, 0x3fb8aa3b, v23
	v_add_f32_e32 v44, v75, v44
	v_exp_f32_e32 v103, v23
	v_sub_f32_e32 v23, v28, v169
	v_add_f32_e32 v44, v76, v44
	v_mul_f32_e32 v23, 0x3fb8aa3b, v23
	v_add_f32_e32 v44, v77, v44
	v_exp_f32_e32 v104, v23
	v_sub_f32_e32 v23, v29, v169
	v_add_f32_e32 v22, v78, v44
	v_mul_f32_e32 v23, 0x3fb8aa3b, v23
	v_add_f32_e32 v22, v79, v22
	v_exp_f32_e32 v105, v23
	v_sub_f32_e32 v23, v30, v169
	v_exp_f32_e32 v159, v17
	v_sub_f32_e32 v17, v170, v169
	v_add_f32_e32 v22, v100, v22
	v_mul_f32_e32 v23, 0x3fb8aa3b, v23
	v_mul_f32_e32 v17, 0x3fb8aa3b, v17
	v_add_f32_e32 v22, v101, v22
	v_exp_f32_e32 v106, v23
	v_sub_f32_e32 v23, v31, v169
	v_exp_f32_e32 v160, v17
	v_sub_f32_e32 v17, v171, v169
	v_add_f32_e32 v22, v102, v22
	v_mul_f32_e32 v23, 0x3fb8aa3b, v23
	v_mul_f32_e32 v17, 0x3fb8aa3b, v17
	v_add_f32_e32 v22, v103, v22
	v_exp_f32_e32 v107, v23
	v_exp_f32_e32 v161, v17
	v_sub_f32_e32 v17, v172, v169
	v_add_f32_e32 v22, v104, v22
	v_mul_f32_e32 v17, 0x3fb8aa3b, v17
	v_add_f32_e32 v22, v105, v22
	v_exp_f32_e32 v109, v21
	v_exp_f32_e32 v162, v17
	v_sub_f32_e32 v17, v173, v169
	v_add_f32_e32 v22, v106, v22
	v_exp_f32_e32 v110, v18
	v_mul_f32_e32 v19, 0x3fb8aa3b, v19
	v_sub_f32_e32 v16, v16, v169
	v_mul_f32_e32 v17, 0x3fb8aa3b, v17
	v_add_f32_e32 v22, v107, v22
	v_exp_f32_e32 v111, v19
	v_mul_f32_e32 v16, 0x3fb8aa3b, v16
	v_exp_f32_e32 v163, v17
	v_sub_f32_e32 v17, v176, v169
	v_add_f32_e32 v20, v108, v22
	v_exp_f32_e32 v158, v16
	v_mul_f32_e32 v17, 0x3fb8aa3b, v17
	v_add_f32_e32 v20, v109, v20
	v_exp_f32_e32 v164, v17
	v_sub_f32_e32 v17, v177, v169
	v_add_f32_e32 v18, v110, v20
	v_mul_f32_e32 v17, 0x3fb8aa3b, v17
	v_add_f32_e32 v18, v111, v18
	v_exp_f32_e32 v165, v17
	v_sub_f32_e32 v17, v178, v169
	v_add_f32_e32 v16, v158, v18
	v_mul_f32_e32 v17, 0x3fb8aa3b, v17
	v_add_f32_e32 v16, v159, v16
	v_exp_f32_e32 v170, v17
	v_sub_f32_e32 v17, v179, v169
	v_add_f32_e32 v16, v160, v16
	v_mul_f32_e32 v17, 0x3fb8aa3b, v17
	v_add_f32_e32 v16, v161, v16
	v_exp_f32_e32 v171, v17
	v_sub_f32_e32 v17, v180, v169
	v_add_f32_e32 v16, v162, v16
	v_mul_f32_e32 v17, 0x3fb8aa3b, v17
	v_add_f32_e32 v16, v163, v16
	v_exp_f32_e32 v172, v17
	v_sub_f32_e32 v17, v116, v169
	v_add_f32_e32 v16, v164, v16
	v_mul_f32_e32 v17, 0x3fb8aa3b, v17
	v_add_f32_e32 v16, v165, v16
	v_exp_f32_e32 v173, v17
	v_add_f32_e32 v16, v170, v16
	v_add_f32_e32 v16, v171, v16
	v_add_f32_e32 v16, v172, v16
	v_add_f32_e32 v16, v173, v16
	ds_bpermute_b32 v17, v144, v16
	s_waitcnt lgkmcnt(0)
	v_add_f32_e32 v16, v16, v17
	v_sub_f32_e32 v17, v147, v169
	v_mul_f32_e32 v17, 0x3fb8aa3b, v17
	v_exp_f32_e32 v17, v17
	s_nop 0
	v_add_f32_e32 v16, v17, v16
	v_rcp_f32_e32 v116, v16
	s_nop 0
	v_pk_mul_f32 v[48:49], v[8:9], v[116:117] op_sel_hi:[1,0]
	v_lshl_add_u32 v8, v157, 1, v156
	v_pk_mul_f32 v[0:1], v[0:1], v[116:117] op_sel_hi:[1,0]
	v_pk_mul_f32 v[2:3], v[2:3], v[116:117] op_sel_hi:[1,0]
	v_pk_mul_f32 v[4:5], v[4:5], v[116:117] op_sel_hi:[1,0]
	v_pk_mul_f32 v[6:7], v[6:7], v[116:117] op_sel_hi:[1,0]
	v_add_u32_e32 v123, 0x9000, v8
	v_cvt_pk_bf16_f32 v0, v0, v1
	v_cvt_pk_bf16_f32 v1, v2, v3
	v_cvt_pk_bf16_f32 v2, v4, v5
	v_cvt_pk_bf16_f32 v3, v6, v7
	ds_read2_b64 v[4:7], v123 offset1:2
	ds_read2_b64 v[44:47], v123 offset0:4 offset1:6
	v_add_u32_e32 v125, 0xd000, v8
	s_waitcnt lgkmcnt(1)
	v_mfma_f32_32x32x16_bf16 v[16:31], v[4:7], v[0:3], 0
	ds_read2_b64 v[4:7], v125 offset0:32 offset1:34
	v_mul_f32_e64 v50, v10, v116
	v_mul_f32_e64 v51, v11, v116
	v_mul_f32_e64 v176, v12, v116
	v_mul_f32_e64 v177, v13, v116
	v_pk_mul_f32 v[178:179], v[14:15], v[116:117] op_sel_hi:[1,0]
	v_pk_mul_f32 v[32:33], v[32:33], v[116:117] op_sel_hi:[1,0]
	v_pk_mul_f32 v[34:35], v[34:35], v[116:117] op_sel_hi:[1,0]
	v_pk_mul_f32 v[36:37], v[36:37], v[116:117] op_sel_hi:[1,0]
	v_pk_mul_f32 v[38:39], v[38:39], v[116:117] op_sel_hi:[1,0]
	v_cvt_pk_bf16_f32 v48, v48, v49
	v_cvt_pk_bf16_f32 v49, v50, v51
	v_cvt_pk_bf16_f32 v50, v176, v177
	v_cvt_pk_bf16_f32 v51, v178, v179
	v_cvt_pk_bf16_f32 v32, v32, v33
	v_cvt_pk_bf16_f32 v33, v34, v35
	v_cvt_pk_bf16_f32 v34, v36, v37
	v_cvt_pk_bf16_f32 v35, v38, v39
	ds_read2_b64 v[36:39], v123 offset0:8 offset1:10
	s_waitcnt lgkmcnt(2)
	v_mfma_f32_32x32x16_bf16 v[16:31], v[44:47], v[48:51], v[16:31]
	ds_read2_b64 v[44:47], v125 offset0:36 offset1:38
	v_mul_f32_e64 v40, v40, v116
	v_mul_f32_e64 v41, v41, v116
	v_mul_f32_e64 v42, v42, v116
	v_mul_f32_e64 v43, v43, v116
	s_waitcnt lgkmcnt(2)
	v_mfma_f32_32x32x16_bf16 v[0:15], v[4:7], v[0:3], 0
	s_waitcnt lgkmcnt(1)
	v_mfma_f32_32x32x16_bf16 v[16:31], v[36:39], v[32:35], v[16:31]
	ds_read2_b64 v[36:39], v125 offset0:40 offset1:42
	s_waitcnt lgkmcnt(1)
	v_mfma_f32_32x32x16_bf16 v[0:15], v[44:47], v[48:51], v[0:15]
	v_mul_f32_e64 v44, v52, v116
	v_mul_f32_e64 v45, v53, v116
	v_mul_f32_e64 v46, v54, v116
	v_mul_f32_e64 v47, v55, v116
	s_waitcnt lgkmcnt(0)
	v_mfma_f32_32x32x16_bf16 v[0:15], v[36:39], v[32:35], v[0:15]
	ds_read2_b64 v[36:39], v123 offset0:12 offset1:14
	v_cvt_pk_bf16_f32 v32, v40, v41
	v_cvt_pk_bf16_f32 v33, v42, v43
	v_cvt_pk_bf16_f32 v34, v44, v45
	v_cvt_pk_bf16_f32 v35, v46, v47
	v_pk_mul_f32 v[40:41], v[64:65], v[116:117] op_sel_hi:[1,0]
	v_pk_mul_f32 v[42:43], v[66:67], v[116:117] op_sel_hi:[1,0]
	s_waitcnt lgkmcnt(0)
	v_mfma_f32_32x32x16_bf16 v[16:31], v[36:39], v[32:35], v[16:31]
	ds_read2_b64 v[36:39], v125 offset0:44 offset1:46
	v_mul_f32_e64 v44, v68, v116
	v_mul_f32_e64 v45, v69, v116
	v_mul_f32_e64 v46, v70, v116
	v_mul_f32_e64 v47, v71, v116
	s_waitcnt lgkmcnt(0)
	v_mfma_f32_32x32x16_bf16 v[0:15], v[36:39], v[32:35], v[0:15]
	v_mul_f32_e64 v32, v56, v116
	v_mul_f32_e64 v33, v57, v116
	v_mul_f32_e64 v34, v58, v116
	v_mul_f32_e64 v35, v59, v116
	v_mul_f32_e64 v36, v60, v116
	v_mul_f32_e64 v37, v61, v116
	v_pk_mul_f32 v[38:39], v[62:63], v[116:117] op_sel_hi:[1,0]
	v_cvt_pk_bf16_f32 v32, v32, v33
	v_cvt_pk_bf16_f32 v33, v34, v35
	v_cvt_pk_bf16_f32 v34, v36, v37
	v_cvt_pk_bf16_f32 v35, v38, v39
	ds_read2_b64 v[36:39], v123 offset0:16 offset1:18
	s_waitcnt lgkmcnt(0)
	v_mfma_f32_32x32x16_bf16 v[16:31], v[36:39], v[32:35], v[16:31]
	ds_read2_b64 v[36:39], v125 offset0:48 offset1:50
	s_waitcnt lgkmcnt(0)
	v_mfma_f32_32x32x16_bf16 v[0:15], v[36:39], v[32:35], v[0:15]
	ds_read2_b64 v[36:39], v123 offset0:20 offset1:22
	v_cvt_pk_bf16_f32 v32, v40, v41
	v_cvt_pk_bf16_f32 v33, v42, v43
	v_cvt_pk_bf16_f32 v34, v44, v45
	v_cvt_pk_bf16_f32 v35, v46, v47
	v_pk_mul_f32 v[40:41], v[100:101], v[116:117] op_sel_hi:[1,0]
	v_pk_mul_f32 v[42:43], v[102:103], v[116:117] op_sel_hi:[1,0]
	s_waitcnt lgkmcnt(0)
	v_mfma_f32_32x32x16_bf16 v[16:31], v[36:39], v[32:35], v[16:31]
	ds_read2_b64 v[36:39], v125 offset0:52 offset1:54
	v_mul_f32_e64 v44, v104, v116
	v_mul_f32_e64 v45, v105, v116
	v_mul_f32_e64 v46, v106, v116
	v_mul_f32_e64 v47, v107, v116
	s_waitcnt vmcnt(10)
	v_mov_b64_e32 v[102:103], v[90:91]
	s_waitcnt vmcnt(9)
	v_mov_b64_e32 v[106:107], v[94:95]
	v_mov_b64_e32 v[100:101], v[88:89]
	v_mov_b64_e32 v[104:105], v[92:93]
	s_waitcnt lgkmcnt(0)
	v_mfma_f32_32x32x16_bf16 v[0:15], v[36:39], v[32:35], v[0:15]
	v_mul_f32_e64 v32, v72, v116
	v_mul_f32_e64 v33, v73, v116
	v_mul_f32_e64 v34, v74, v116
	v_mul_f32_e64 v35, v75, v116
	v_mul_f32_e64 v36, v76, v116
	v_mul_f32_e64 v37, v77, v116
	v_pk_mul_f32 v[38:39], v[78:79], v[116:117] op_sel_hi:[1,0]
	v_cvt_pk_bf16_f32 v32, v32, v33
	v_cvt_pk_bf16_f32 v33, v34, v35
	v_cvt_pk_bf16_f32 v34, v36, v37
	v_cvt_pk_bf16_f32 v35, v38, v39
	ds_read2_b64 v[36:39], v123 offset0:24 offset1:26
	s_waitcnt lgkmcnt(0)
	v_mfma_f32_32x32x16_bf16 v[16:31], v[36:39], v[32:35], v[16:31]
	ds_read2_b64 v[36:39], v125 offset0:56 offset1:58
	s_waitcnt lgkmcnt(0)
	v_mfma_f32_32x32x16_bf16 v[0:15], v[36:39], v[32:35], v[0:15]
	ds_read2_b64 v[36:39], v123 offset0:28 offset1:30
	v_cvt_pk_bf16_f32 v32, v40, v41
	v_cvt_pk_bf16_f32 v33, v42, v43
	v_cvt_pk_bf16_f32 v34, v44, v45
	v_cvt_pk_bf16_f32 v35, v46, v47
	v_pk_mul_f32 v[40:41], v[162:163], v[116:117] op_sel_hi:[1,0]
	v_pk_mul_f32 v[42:43], v[164:165], v[116:117] op_sel_hi:[1,0]
	s_waitcnt lgkmcnt(0)
	v_mfma_f32_32x32x16_bf16 v[16:31], v[36:39], v[32:35], v[16:31]
	ds_read2_b64 v[36:39], v125 offset0:60 offset1:62
	v_mul_f32_e64 v44, v170, v116
	v_mul_f32_e64 v45, v171, v116
	v_mul_f32_e64 v46, v172, v116
	v_mul_f32_e64 v47, v173, v116
	s_waitcnt lgkmcnt(0)
	v_mfma_f32_32x32x16_bf16 v[0:15], v[36:39], v[32:35], v[0:15]
	v_mul_f32_e64 v32, v108, v116
	v_mul_f32_e64 v33, v109, v116
	v_mul_f32_e64 v34, v110, v116
	v_mul_f32_e64 v35, v111, v116
	v_mul_f32_e64 v36, v158, v116
	v_mul_f32_e64 v37, v159, v116
	v_pk_mul_f32 v[38:39], v[160:161], v[116:117] op_sel_hi:[1,0]
	v_cvt_pk_bf16_f32 v32, v32, v33
	v_cvt_pk_bf16_f32 v33, v34, v35
	v_cvt_pk_bf16_f32 v34, v36, v37
	v_cvt_pk_bf16_f32 v35, v38, v39
	ds_read2_b64 v[36:39], v123 offset0:32 offset1:34
	s_waitcnt vmcnt(8)
	v_mov_b64_e32 v[110:111], v[98:99]
	s_waitcnt lgkmcnt(0)
	v_mfma_f32_32x32x16_bf16 v[16:31], v[36:39], v[32:35], v[16:31]
	ds_read2_b64 v[36:39], v125 offset0:64 offset1:66
	v_mov_b64_e32 v[108:109], v[96:97]
	s_waitcnt lgkmcnt(0)
	v_mfma_f32_32x32x16_bf16 v[0:15], v[36:39], v[32:35], v[0:15]
	ds_read2_b64 v[36:39], v123 offset0:36 offset1:38
	v_cvt_pk_bf16_f32 v32, v40, v41
	v_cvt_pk_bf16_f32 v33, v42, v43
	v_cvt_pk_bf16_f32 v34, v44, v45
	v_cvt_pk_bf16_f32 v35, v46, v47
	s_waitcnt lgkmcnt(0)
	s_nop 0
	v_mfma_f32_32x32x16_bf16 v[16:31], v[36:39], v[32:35], v[16:31]
	ds_read2_b64 v[36:39], v125 offset0:68 offset1:70
	s_waitcnt lgkmcnt(0)
	v_mfma_f32_32x32x16_bf16 v[0:15], v[36:39], v[32:35], v[0:15]
	s_waitcnt vmcnt(7)
	v_lshlrev_b32_e32 v34, 16, v142
	v_and_b32_e32 v35, 0xffff0000, v142
	v_mul_f32_e32 v36, 0xbfb8aa3b, v34
	v_mul_f32_e32 v37, 0xbfb8aa3b, v35
	v_exp_f32_e32 v36, v36
	v_exp_f32_e32 v37, v37
	v_lshlrev_b64 v[32:33], 10, v[140:141]
	v_add_f32_e32 v36, 1.0, v36
	v_add_f32_e32 v37, 1.0, v37
	v_rcp_f32_e32 v36, v36
	v_rcp_f32_e32 v37, v37
	s_nop 0
	v_pk_mul_f32 v[34:35], v[36:37], v[34:35]
	s_nop 0
	v_pk_mul_f32 v[16:17], v[34:35], v[16:17]
	v_lshlrev_b32_e32 v34, 16, v143
	v_cvt_pk_bf16_f32 v16, v16, v17
	v_mul_f32_e32 v17, 0xbfb8aa3b, v34
	v_exp_f32_e32 v17, v17
	v_and_b32_e32 v35, 0xffff0000, v143
	v_add_f32_e32 v17, 1.0, v17
	v_rcp_f32_e32 v36, v17
	v_mul_f32_e32 v17, 0xbfb8aa3b, v35
	v_exp_f32_e32 v17, v17
	s_nop 0
	v_add_f32_e32 v17, 1.0, v17
	v_rcp_f32_e32 v37, v17
	s_nop 0
	v_pk_mul_f32 v[34:35], v[36:37], v[34:35]
	s_nop 0
	v_pk_mul_f32 v[18:19], v[34:35], v[18:19]
	s_nop 0
	v_cvt_pk_bf16_f32 v17, v18, v19
	v_lshl_add_u64 v[18:19], v[120:121], 0, v[32:33]
	global_store_dwordx2 v[18:19], v[16:17], off
	s_waitcnt vmcnt(7)
	v_lshlrev_b32_e32 v16, 16, v138
	v_and_b32_e32 v17, 0xffff0000, v138
	v_mul_f32_e32 v32, 0xbfb8aa3b, v16
	v_mul_f32_e32 v33, 0xbfb8aa3b, v17
	v_exp_f32_e32 v32, v32
	v_exp_f32_e32 v33, v33
	v_add_f32_e32 v32, 1.0, v32
	v_add_f32_e32 v33, 1.0, v33
	v_rcp_f32_e32 v32, v32
	v_rcp_f32_e32 v33, v33
	s_nop 0
	v_pk_mul_f32 v[16:17], v[32:33], v[16:17]
	s_nop 0
	v_pk_mul_f32 v[16:17], v[16:17], v[20:21]
	v_lshlrev_b32_e32 v20, 16, v139
	v_cvt_pk_bf16_f32 v16, v16, v17
	v_mul_f32_e32 v17, 0xbfb8aa3b, v20
	v_exp_f32_e32 v17, v17
	v_and_b32_e32 v21, 0xffff0000, v139
	v_add_f32_e32 v17, 1.0, v17
	v_rcp_f32_e32 v32, v17
	v_mul_f32_e32 v17, 0xbfb8aa3b, v21
	v_exp_f32_e32 v17, v17
	s_nop 0
	v_add_f32_e32 v17, 1.0, v17
	v_rcp_f32_e32 v33, v17
	s_nop 0
	v_pk_mul_f32 v[20:21], v[32:33], v[20:21]
	s_nop 0
	v_pk_mul_f32 v[20:21], v[20:21], v[22:23]
	s_nop 0
	v_cvt_pk_bf16_f32 v17, v20, v21
	global_store_dwordx2 v[18:19], v[16:17], off offset:16
	s_waitcnt vmcnt(7)
	v_lshlrev_b32_e32 v16, 16, v136
	v_and_b32_e32 v17, 0xffff0000, v136
	v_mul_f32_e32 v20, 0xbfb8aa3b, v16
	v_mul_f32_e32 v21, 0xbfb8aa3b, v17
	v_exp_f32_e32 v20, v20
	v_exp_f32_e32 v21, v21
	v_add_f32_e32 v20, 1.0, v20
	v_add_f32_e32 v21, 1.0, v21
	v_rcp_f32_e32 v20, v20
	v_rcp_f32_e32 v21, v21
	s_nop 0
	v_pk_mul_f32 v[16:17], v[20:21], v[16:17]
	s_nop 0
	v_pk_mul_f32 v[16:17], v[16:17], v[24:25]
	v_lshlrev_b32_e32 v20, 16, v137
	v_cvt_pk_bf16_f32 v16, v16, v17
	v_mul_f32_e32 v17, 0xbfb8aa3b, v20
	v_exp_f32_e32 v17, v17
	v_and_b32_e32 v21, 0xffff0000, v137
	v_add_f32_e32 v17, 1.0, v17
	v_rcp_f32_e32 v22, v17
	v_mul_f32_e32 v17, 0xbfb8aa3b, v21
	v_exp_f32_e32 v17, v17
	s_nop 0
	v_add_f32_e32 v17, 1.0, v17
	v_rcp_f32_e32 v23, v17
	s_nop 0
	v_pk_mul_f32 v[20:21], v[22:23], v[20:21]
	s_nop 0
	v_pk_mul_f32 v[20:21], v[20:21], v[26:27]
	s_nop 0
	v_cvt_pk_bf16_f32 v17, v20, v21
	global_store_dwordx2 v[18:19], v[16:17], off offset:32
	s_waitcnt vmcnt(7)
	v_lshlrev_b32_e32 v16, 16, v134
	v_and_b32_e32 v17, 0xffff0000, v134
	v_mul_f32_e32 v20, 0xbfb8aa3b, v16
	v_mul_f32_e32 v21, 0xbfb8aa3b, v17
	v_exp_f32_e32 v20, v20
	v_exp_f32_e32 v21, v21
	v_add_f32_e32 v20, 1.0, v20
	v_add_f32_e32 v21, 1.0, v21
	v_rcp_f32_e32 v20, v20
	v_rcp_f32_e32 v21, v21
	s_nop 0
	v_pk_mul_f32 v[16:17], v[20:21], v[16:17]
	s_nop 0
	v_pk_mul_f32 v[16:17], v[16:17], v[28:29]
	v_lshlrev_b32_e32 v20, 16, v135
	v_cvt_pk_bf16_f32 v16, v16, v17
	v_mul_f32_e32 v17, 0xbfb8aa3b, v20
	v_exp_f32_e32 v17, v17
	v_and_b32_e32 v21, 0xffff0000, v135
	v_add_f32_e32 v17, 1.0, v17
	v_rcp_f32_e32 v22, v17
	v_mul_f32_e32 v17, 0xbfb8aa3b, v21
	v_exp_f32_e32 v17, v17
	s_nop 0
	v_add_f32_e32 v17, 1.0, v17
	v_rcp_f32_e32 v23, v17
	s_nop 0
	v_pk_mul_f32 v[20:21], v[22:23], v[20:21]
	s_nop 0
	v_pk_mul_f32 v[20:21], v[20:21], v[30:31]
	s_nop 0
	v_cvt_pk_bf16_f32 v17, v20, v21
	global_store_dwordx2 v[18:19], v[16:17], off offset:48
	s_waitcnt vmcnt(7)
	v_lshlrev_b32_e32 v16, 16, v132
	v_and_b32_e32 v17, 0xffff0000, v132
	v_mul_f32_e32 v20, 0xbfb8aa3b, v16
	v_mul_f32_e32 v21, 0xbfb8aa3b, v17
	v_exp_f32_e32 v20, v20
	v_exp_f32_e32 v21, v21
	v_add_f32_e32 v20, 1.0, v20
	v_add_f32_e32 v21, 1.0, v21
	v_rcp_f32_e32 v20, v20
	v_rcp_f32_e32 v21, v21
	s_nop 0
	v_pk_mul_f32 v[16:17], v[20:21], v[16:17]
	s_nop 0
	v_pk_mul_f32 v[0:1], v[16:17], v[0:1]
	v_lshlrev_b32_e32 v16, 16, v133
	v_cvt_pk_bf16_f32 v0, v0, v1
	v_mul_f32_e32 v1, 0xbfb8aa3b, v16
	v_exp_f32_e32 v1, v1
	v_and_b32_e32 v17, 0xffff0000, v133
	v_add_f32_e32 v1, 1.0, v1
	v_rcp_f32_e32 v20, v1
	v_mul_f32_e32 v1, 0xbfb8aa3b, v17
	v_exp_f32_e32 v1, v1
	s_nop 0
	v_add_f32_e32 v1, 1.0, v1
	v_rcp_f32_e32 v21, v1
	s_nop 0
	v_pk_mul_f32 v[16:17], v[20:21], v[16:17]
	s_nop 0
	v_pk_mul_f32 v[2:3], v[16:17], v[2:3]
	s_nop 0
	v_cvt_pk_bf16_f32 v1, v2, v3
	global_store_dwordx2 v[18:19], v[0:1], off offset:64
	s_waitcnt vmcnt(7)
	v_lshlrev_b32_e32 v0, 16, v130
	v_and_b32_e32 v1, 0xffff0000, v130
	v_mul_f32_e32 v2, 0xbfb8aa3b, v0
	v_mul_f32_e32 v3, 0xbfb8aa3b, v1
	v_exp_f32_e32 v2, v2
	v_exp_f32_e32 v3, v3
	v_add_f32_e32 v2, 1.0, v2
	v_add_f32_e32 v3, 1.0, v3
	v_rcp_f32_e32 v2, v2
	v_rcp_f32_e32 v3, v3
	s_nop 0
	v_pk_mul_f32 v[0:1], v[2:3], v[0:1]
	s_nop 0
	v_pk_mul_f32 v[0:1], v[0:1], v[4:5]
	v_lshlrev_b32_e32 v2, 16, v131
	v_cvt_pk_bf16_f32 v0, v0, v1
	v_mul_f32_e32 v1, 0xbfb8aa3b, v2
	v_exp_f32_e32 v1, v1
	v_and_b32_e32 v3, 0xffff0000, v131
	v_add_f32_e32 v1, 1.0, v1
	v_rcp_f32_e32 v4, v1
	v_mul_f32_e32 v1, 0xbfb8aa3b, v3
	v_exp_f32_e32 v1, v1
	s_nop 0
	v_add_f32_e32 v1, 1.0, v1
	v_rcp_f32_e32 v5, v1
	s_nop 0
	v_pk_mul_f32 v[2:3], v[4:5], v[2:3]
	s_nop 0
	v_pk_mul_f32 v[2:3], v[2:3], v[6:7]
	s_nop 0
	v_cvt_pk_bf16_f32 v1, v2, v3
	global_store_dwordx2 v[18:19], v[0:1], off offset:80
	s_waitcnt vmcnt(7)
	v_lshlrev_b32_e32 v0, 16, v128
	v_and_b32_e32 v1, 0xffff0000, v128
	v_mul_f32_e32 v2, 0xbfb8aa3b, v0
	v_mul_f32_e32 v3, 0xbfb8aa3b, v1
	v_exp_f32_e32 v2, v2
	v_exp_f32_e32 v3, v3
	v_add_f32_e32 v2, 1.0, v2
	v_add_f32_e32 v3, 1.0, v3
	v_rcp_f32_e32 v2, v2
	v_rcp_f32_e32 v3, v3
	s_nop 0
	v_pk_mul_f32 v[0:1], v[2:3], v[0:1]
	s_nop 0
	v_pk_mul_f32 v[0:1], v[0:1], v[8:9]
	v_lshlrev_b32_e32 v2, 16, v129
	v_cvt_pk_bf16_f32 v0, v0, v1
	v_mul_f32_e32 v1, 0xbfb8aa3b, v2
	v_exp_f32_e32 v1, v1
	v_and_b32_e32 v3, 0xffff0000, v129
	v_add_f32_e32 v1, 1.0, v1
	v_rcp_f32_e32 v4, v1
	v_mul_f32_e32 v1, 0xbfb8aa3b, v3
	v_exp_f32_e32 v1, v1
	s_nop 0
	v_add_f32_e32 v1, 1.0, v1
	v_rcp_f32_e32 v5, v1
	s_nop 0
	v_pk_mul_f32 v[2:3], v[4:5], v[2:3]
	s_nop 0
	v_pk_mul_f32 v[2:3], v[2:3], v[10:11]
	s_nop 0
	v_cvt_pk_bf16_f32 v1, v2, v3
	global_store_dwordx2 v[18:19], v[0:1], off offset:96
	s_waitcnt vmcnt(7)
	v_lshlrev_b32_e32 v0, 16, v126
	v_and_b32_e32 v1, 0xffff0000, v126
	v_mul_f32_e32 v2, 0xbfb8aa3b, v0
	v_mul_f32_e32 v3, 0xbfb8aa3b, v1
	v_exp_f32_e32 v2, v2
	v_exp_f32_e32 v3, v3
	v_add_f32_e32 v2, 1.0, v2
	v_add_f32_e32 v3, 1.0, v3
	v_rcp_f32_e32 v2, v2
	v_rcp_f32_e32 v3, v3
	s_nop 0
	v_pk_mul_f32 v[0:1], v[2:3], v[0:1]
	s_nop 0
	v_pk_mul_f32 v[0:1], v[0:1], v[12:13]
	v_lshlrev_b32_e32 v2, 16, v127
	v_cvt_pk_bf16_f32 v0, v0, v1
	v_mul_f32_e32 v1, 0xbfb8aa3b, v2
	v_exp_f32_e32 v1, v1
	v_and_b32_e32 v3, 0xffff0000, v127
	v_add_f32_e32 v1, 1.0, v1
	v_rcp_f32_e32 v4, v1
	v_mul_f32_e32 v1, 0xbfb8aa3b, v3
	v_exp_f32_e32 v1, v1
	s_nop 0
	v_add_f32_e32 v1, 1.0, v1
	v_rcp_f32_e32 v5, v1
	s_nop 0
	v_pk_mul_f32 v[2:3], v[4:5], v[2:3]
	s_nop 0
	v_pk_mul_f32 v[2:3], v[2:3], v[14:15]
	s_nop 0
	v_cvt_pk_bf16_f32 v1, v2, v3
	global_store_dwordx2 v[18:19], v[0:1], off offset:112
	v_mov_b64_e32 v[0:1], v[84:85]
	v_mov_b64_e32 v[2:3], v[86:87]
	s_cbranch_vccnz .LBB0_302
	s_add_i32 s86, s86, s0
	s_mov_b32 s66, s0
	s_cmpk_lt_i32 s86, 0x100
	s_mov_b64 s[62:63], s[78:79]
	s_mov_b64 s[64:65], s[2:3]
	s_movk_i32 s53, 0x2000
	s_mov_b32 s58, 0x800000
	s_movk_i32 s69, 0x410
	s_movk_i32 s52, 0x880
	s_movk_i32 s50, 0x110
	v_readlane_b32 s51, v254, 48
	s_mov_b32 s47, 0x28000
	v_readlane_b32 s83, v255, 3
	s_mov_b32 s36, s33
	s_mov_b32 s33, 0x48000
	v_readlane_b32 s37, v255, 4
	s_barrier
	s_cbranch_scc1 .LBB0_287
	s_mov_b32 s5, s64
	v_readlane_b32 s0, v254, 55
	s_mov_b32 s3, 0x42ce8ed0
	s_mov_b32 s20, 0xc2b17218
	v_readlane_b32 s21, v254, 40
	s_mov_b64 s[12:13], 0x23cc2800
